# E50: barrier spin loops poll back-to-back (s_sleep removed) for faster release detection
# speedup vs baseline: 1.0002x; 1.0002x over previous
; __global__ void __launch_bounds__(512, 2) fwd_kernel(Args a_byval) {
;     ...
;     if (hi > 1000) cg::this_grid().sync();
.LBB0_16:
	global_load_dword v2, v0, s[4:5] offset:32 sc1
	s_waitcnt vmcnt(0)
	v_and_b32_e32 v2, 0xffff0000, v2
	v_cmp_ne_u32_e32 vcc, v2, v1
	s_or_b64 s[6:7], vcc, s[6:7]
	s_andn2_b64 exec, exec, s[6:7]
	s_cbranch_execnz .LBB0_16

; DI unsigned xb_ld(unsigned* p)              { return __hip_atomic_load(p, __ATOMIC_RELAXED, __HIP_MEMORY_SCOPE_AGENT); }
; DI void xcd_barrier_complete(unsigned* bar, unsigned x, unsigned& nloc, unsigned& nx) {
;     ...
;     for (;;) {
;         sum = 0u; cnt = 0u; mine = 0u;
; #pragma unroll
;         for (unsigned j = 0; j < 16; ++j) { const unsigned c = xb_ld(&bar[XB_XCNT(j)]); sum += c; cnt += (c > 0u) ? 1u : 0u; mine = (j == x) ? c : mine; }
;         if (sum == G) break;
;         __builtin_amdgcn_s_sleep(1);
;         if ((++sp & 255u) == 0u) { if (xb_ld(&bar[XB_TMO])) break; if (sp > XB_SPIN_CAP) { atomicAdd(&bar[XB_TMO], 1u); break; } }
;     }
.LBB0_46:
	global_load_dword v15, v16, s[8:9] sc1
	global_load_dword v0, v16, s[10:11] sc1
	global_load_dword v1, v16, s[12:13] sc1
	global_load_dword v2, v16, s[14:15] sc1
	global_load_dword v3, v16, s[16:17] sc1
	global_load_dword v4, v16, s[18:19] sc1
	global_load_dword v5, v16, s[20:21] sc1
	global_load_dword v6, v16, s[22:23] sc1
	global_load_dword v7, v16, s[24:25] sc1
	global_load_dword v8, v16, s[26:27] sc1
	global_load_dword v9, v16, s[28:29] sc1
	global_load_dword v10, v16, s[30:31] sc1
	global_load_dword v11, v16, s[34:35] sc1
	global_load_dword v12, v16, s[42:43] sc1
	global_load_dword v13, v16, s[44:45] sc1
	global_load_dword v14, v16, s[46:47] sc1
	s_mov_b64 s[48:49], -1
	s_mov_b64 s[50:51], -1
	s_waitcnt vmcnt(14)
	v_add_u32_e32 v17, v0, v15
	s_waitcnt vmcnt(13)
	v_add_u32_e32 v17, v17, v1
	s_waitcnt vmcnt(12)
	v_add_u32_e32 v17, v17, v2
	s_waitcnt vmcnt(11)
	v_add_u32_e32 v17, v17, v3
	s_waitcnt vmcnt(10)
	v_add_u32_e32 v17, v17, v4
	s_waitcnt vmcnt(9)
	v_add_u32_e32 v17, v17, v5
	s_waitcnt vmcnt(8)
	v_add_u32_e32 v17, v17, v6
	s_waitcnt vmcnt(7)
	v_add_u32_e32 v17, v17, v7
	s_waitcnt vmcnt(6)
	v_add_u32_e32 v17, v17, v8
	s_waitcnt vmcnt(5)
	v_add_u32_e32 v17, v17, v9
	s_waitcnt vmcnt(4)
	v_add_u32_e32 v17, v17, v10
	s_waitcnt vmcnt(3)
	v_add_u32_e32 v17, v17, v11
	s_waitcnt vmcnt(2)
	v_add_u32_e32 v17, v17, v12
	s_waitcnt vmcnt(1)
	v_add_u32_e32 v17, v17, v13
	s_waitcnt vmcnt(0)
	v_add_u32_e32 v17, v17, v14
	v_cmp_eq_u32_e32 vcc, s33, v17
	s_cbranch_vccnz .LBB0_45
	s_and_b32 s48, s54, 0xff
	s_cmp_eq_u32 s48, 0
	s_mov_b64 s[48:49], -1
	s_mov_b64 s[52:53], -1
	s_cbranch_scc1 .LBB0_50
	s_and_b64 vcc, exec, s[52:53]
	s_cbranch_vccz .LBB0_45

; DI unsigned xb_ld(unsigned* p)              { return __hip_atomic_load(p, __ATOMIC_RELAXED, __HIP_MEMORY_SCOPE_AGENT); }
; #define XB_SPIN(cond, bar) do { unsigned _sp = 0; while (cond) { __builtin_amdgcn_s_sleep(1); \
;     if ((++_sp & 255u) == 0u) { if (xb_ld(&(bar)[XB_TMO])) break; if (_sp > XB_SPIN_CAP) { atomicAdd(&(bar)[XB_TMO], 1u); break; } } } } while (0)
; DI void xcd_barrier(const XcdBarrier& b) {
;     ...
;             XB_SPIN(xb_ld(&bar[XB_XGEN(b.x)]) == gen, bar);
.LBB0_62:
	s_and_b32 s20, s24, 0xff
	s_mov_b64 s[18:19], -1
	s_cmp_lg_u32 s20, 0
	s_mov_b64 s[22:23], -1
	s_cbranch_scc0 .LBB0_65
	s_and_b64 vcc, exec, s[22:23]
	s_cbranch_vccz .LBB0_61

; DI unsigned xb_ld(unsigned* p)              { return __hip_atomic_load(p, __ATOMIC_RELAXED, __HIP_MEMORY_SCOPE_AGENT); }
; #define XB_SPIN(cond, bar) do { unsigned _sp = 0; while (cond) { __builtin_amdgcn_s_sleep(1); \
;     if ((++_sp & 255u) == 0u) { if (xb_ld(&(bar)[XB_TMO])) break; if (_sp > XB_SPIN_CAP) { atomicAdd(&(bar)[XB_TMO], 1u); break; } } } } while (0)
; DI void xcd_barrier(const XcdBarrier& b) {
;     ...
;             else XB_SPIN(xb_ld(&bar[XB_TOPGEN]) == tg, bar);
.LBB0_79:
	s_and_b32 s20, s26, 0xff
	s_cmp_lg_u32 s20, 0
	s_mov_b64 s[22:23], -1
	s_cbranch_scc0 .LBB0_82
	s_mov_b64 s[24:25], -1
	s_and_b64 vcc, exec, s[22:23]
	s_cbranch_vccz .LBB0_78

; DI unsigned xb_ld(unsigned* p)              { return __hip_atomic_load(p, __ATOMIC_RELAXED, __HIP_MEMORY_SCOPE_AGENT); }
; DI void xcd_barrier_complete(unsigned* bar, unsigned x, unsigned& nloc, unsigned& nx) {
;     ...
;     for (;;) {
;         sum = 0u; cnt = 0u; mine = 0u;
; #pragma unroll
;         for (unsigned j = 0; j < 16; ++j) { const unsigned c = xb_ld(&bar[XB_XCNT(j)]); sum += c; cnt += (c > 0u) ? 1u : 0u; mine = (j == x) ? c : mine; }
;         if (sum == G) break;
;         __builtin_amdgcn_s_sleep(1);
;         if ((++sp & 255u) == 0u) { if (xb_ld(&bar[XB_TMO])) break; if (sp > XB_SPIN_CAP) { atomicAdd(&bar[XB_TMO], 1u); break; } }
;     }
.LBB0_717:
	global_load_dword v15, v16, s[8:9] sc1
	global_load_dword v0, v16, s[10:11] sc1
	global_load_dword v1, v16, s[12:13] sc1
	global_load_dword v2, v16, s[14:15] sc1
	global_load_dword v3, v16, s[16:17] sc1
	global_load_dword v4, v16, s[18:19] sc1
	global_load_dword v5, v16, s[20:21] sc1
	global_load_dword v6, v16, s[22:23] sc1
	global_load_dword v7, v16, s[24:25] sc1
	global_load_dword v8, v16, s[26:27] sc1
	global_load_dword v9, v16, s[28:29] sc1
	global_load_dword v10, v16, s[30:31] sc1
	global_load_dword v11, v16, s[34:35] sc1
	global_load_dword v12, v16, s[42:43] sc1
	global_load_dword v13, v16, s[44:45] sc1
	global_load_dword v14, v16, s[46:47] sc1
	s_mov_b64 s[48:49], -1
	s_mov_b64 s[50:51], -1
	s_waitcnt vmcnt(14)
	v_add_u32_e32 v17, v0, v15
	s_waitcnt vmcnt(13)
	v_add_u32_e32 v17, v17, v1
	s_waitcnt vmcnt(12)
	v_add_u32_e32 v17, v17, v2
	s_waitcnt vmcnt(11)
	v_add_u32_e32 v17, v17, v3
	s_waitcnt vmcnt(10)
	v_add_u32_e32 v17, v17, v4
	s_waitcnt vmcnt(9)
	v_add_u32_e32 v17, v17, v5
	s_waitcnt vmcnt(8)
	v_add_u32_e32 v17, v17, v6
	s_waitcnt vmcnt(7)
	v_add_u32_e32 v17, v17, v7
	s_waitcnt vmcnt(6)
	v_add_u32_e32 v17, v17, v8
	s_waitcnt vmcnt(5)
	v_add_u32_e32 v17, v17, v9
	s_waitcnt vmcnt(4)
	v_add_u32_e32 v17, v17, v10
	s_waitcnt vmcnt(3)
	v_add_u32_e32 v17, v17, v11
	s_waitcnt vmcnt(2)
	v_add_u32_e32 v17, v17, v12
	s_waitcnt vmcnt(1)
	v_add_u32_e32 v17, v17, v13
	s_waitcnt vmcnt(0)
	v_add_u32_e32 v17, v17, v14
	v_cmp_eq_u32_e32 vcc, s33, v17
	s_cbranch_vccnz .LBB0_716
	s_and_b32 s48, s39, 0xff
	s_cmp_eq_u32 s48, 0
	s_mov_b64 s[48:49], -1
	s_mov_b64 s[52:53], -1
	s_cbranch_scc1 .LBB0_721
	s_and_b64 vcc, exec, s[52:53]
	s_cbranch_vccz .LBB0_716

; DI unsigned xb_ld(unsigned* p)              { return __hip_atomic_load(p, __ATOMIC_RELAXED, __HIP_MEMORY_SCOPE_AGENT); }
; DI void xcd_barrier_complete(unsigned* bar, unsigned x, unsigned& nloc, unsigned& nx) {
;     ...
;     for (;;) {
;         sum = 0u; cnt = 0u; mine = 0u;
; #pragma unroll
;         for (unsigned j = 0; j < 16; ++j) { const unsigned c = xb_ld(&bar[XB_XCNT(j)]); sum += c; cnt += (c > 0u) ? 1u : 0u; mine = (j == x) ? c : mine; }
;         if (sum == G) break;
;         __builtin_amdgcn_s_sleep(1);
;         if ((++sp & 255u) == 0u) { if (xb_ld(&bar[XB_TMO])) break; if (sp > XB_SPIN_CAP) { atomicAdd(&bar[XB_TMO], 1u); break; } }
;     }
.LBB0_993:
	v_readlane_b32 s4, v253, 14
	v_readlane_b32 s5, v253, 15
	global_load_dword v12, v173, s[64:65] sc1
	global_load_dword v0, v173, s[66:67] sc1
	global_load_dword v1, v173, s[68:69] sc1
	global_load_dword v2, v173, s[70:71] sc1
	global_load_dword v3, v173, s[72:73] sc1
	global_load_dword v4, v173, s[74:75] sc1
	global_load_dword v5, v173, s[76:77] sc1
	global_load_dword v6, v173, s[78:79] sc1
	global_load_dword v7, v173, s[80:81] sc1
	global_load_dword v8, v173, s[20:21] sc1
	global_load_dword v9, v173, s[22:23] sc1
	global_load_dword v10, v173, s[24:25] sc1
	global_load_dword v11, v173, s[14:15] sc1
	global_load_dword v13, v173, s[4:5] sc1
	v_readlane_b32 s4, v253, 16
	v_readlane_b32 s5, v253, 17
	s_mov_b64 s[6:7], -1
	s_waitcnt vmcnt(12)
	v_add_u32_e32 v16, v0, v12
	s_nop 1
	global_load_dword v14, v173, s[4:5] sc1
	v_readlane_b32 s4, v253, 18
	v_readlane_b32 s5, v253, 19
	s_waitcnt vmcnt(12)
	v_add_u32_e32 v16, v16, v1
	s_waitcnt vmcnt(11)
	v_add_u32_e32 v16, v16, v2
	s_waitcnt vmcnt(10)
	v_add_u32_e32 v16, v16, v3
	s_waitcnt vmcnt(9)
	v_add_u32_e32 v16, v16, v4
	s_waitcnt vmcnt(8)
	v_add_u32_e32 v16, v16, v5
	global_load_dword v15, v173, s[4:5] sc1
	s_waitcnt vmcnt(8)
	v_add_u32_e32 v16, v16, v6
	s_waitcnt vmcnt(7)
	v_add_u32_e32 v16, v16, v7
	s_waitcnt vmcnt(6)
	v_add_u32_e32 v16, v16, v8
	s_waitcnt vmcnt(5)
	v_add_u32_e32 v16, v16, v9
	s_waitcnt vmcnt(4)
	v_add_u32_e32 v16, v16, v10
	s_waitcnt vmcnt(3)
	v_add_u32_e32 v16, v16, v11
	s_waitcnt vmcnt(2)
	v_add_u32_e32 v16, v16, v13
	s_mov_b64 s[4:5], -1
	s_waitcnt vmcnt(1)
	v_add_u32_e32 v16, v16, v14
	s_waitcnt vmcnt(0)
	v_add_u32_e32 v16, v16, v15
	v_cmp_eq_u32_e32 vcc, s10, v16
	s_cbranch_vccnz .LBB0_992
	s_and_b32 s4, s11, 0xff
	s_cmp_eq_u32 s4, 0
	s_mov_b64 s[4:5], -1
	s_mov_b64 s[8:9], -1
	s_cbranch_scc1 .LBB0_997
	s_and_b64 vcc, exec, s[8:9]
	s_cbranch_vccz .LBB0_992

; DI unsigned xb_ld(unsigned* p)              { return __hip_atomic_load(p, __ATOMIC_RELAXED, __HIP_MEMORY_SCOPE_AGENT); }
; #define XB_SPIN(cond, bar) do { unsigned _sp = 0; while (cond) { __builtin_amdgcn_s_sleep(1); \
;     if ((++_sp & 255u) == 0u) { if (xb_ld(&(bar)[XB_TMO])) break; if (_sp > XB_SPIN_CAP) { atomicAdd(&(bar)[XB_TMO], 1u); break; } } } } while (0)
; DI void xcd_barrier(const XcdBarrier& b) {
;     ...
;             XB_SPIN(xb_ld(&bar[XB_XGEN(b.x)]) == gen, bar);
.LBB0_1009:
	s_and_b32 s14, s18, 0xff
	s_mov_b64 s[12:13], -1
	s_cmp_lg_u32 s14, 0
	s_mov_b64 s[16:17], -1
	s_cbranch_scc0 .LBB0_1012
	s_and_b64 vcc, exec, s[16:17]
	s_cbranch_vccz .LBB0_1008
